# MLA loop: v_pk_add_f32 row-sum accumulation split into scalar v_add_f32 pairs (28 sites)
# baseline (speedup 1.0000x reference)
.LBB0_527:
	ds_read_b64_tr_b16 v[68:69], v214 offset:28672
	ds_read_b64_tr_b16 v[70:71], v214 offset:29184
	ds_read_b64_tr_b16 v[72:73], v214 offset:29696
	ds_read_b64_tr_b16 v[74:75], v214 offset:30208
	ds_read_b64_tr_b16 v[76:77], v214 offset:30720
	ds_read_b64_tr_b16 v[78:79], v214 offset:31232
	ds_read_b64_tr_b16 v[98:99], v214 offset:31744
	ds_read_b64_tr_b16 v[100:101], v214 offset:32256
	s_add_i32 s13, s13, 1
	v_exp_f32_e32 v67, v50
	v_exp_f32_e32 v134, v82
	v_exp_f32_e32 v135, v51
	v_exp_f32_e32 v136, v83
	v_exp_f32_e32 v52, v52
	v_exp_f32_e32 v137, v84
	v_exp_f32_e32 v53, v53
	v_exp_f32_e32 v138, v85
	v_add_f32_e32 v50, 0, v67
	v_add_f32_e32 v80, 0, v134
	v_add_f32_e32 v50, v135, v50
	v_add_f32_e32 v51, v136, v80
	v_add_f32_e32 v50, v52, v50
	v_add_f32_e32 v80, v137, v51
	v_add_f32_e32 v51, v53, v50
	v_add_f32_e32 v50, v138, v80
	v_exp_f32_e32 v81, v54
	v_exp_f32_e32 v80, v86
	v_exp_f32_e32 v83, v55
	v_exp_f32_e32 v82, v87
	v_exp_f32_e32 v85, v56
	v_exp_f32_e32 v84, v88
	v_exp_f32_e32 v87, v57
	v_exp_f32_e32 v86, v89
	v_exp_f32_e32 v89, v58
	v_exp_f32_e32 v88, v90
	v_add_f32_e32 v50, v80, v50
	v_add_f32_e32 v51, v81, v51
	v_exp_f32_e32 v103, v59
	v_exp_f32_e32 v102, v91
	v_add_f32_e32 v50, v82, v50
	v_add_f32_e32 v51, v83, v51
	v_exp_f32_e32 v91, v60
	v_exp_f32_e32 v90, v92
	v_add_f32_e32 v50, v84, v50
	v_add_f32_e32 v51, v85, v51
	v_exp_f32_e32 v105, v61
	v_exp_f32_e32 v104, v93
	v_add_f32_e32 v50, v86, v50
	v_add_f32_e32 v51, v87, v51
	v_exp_f32_e32 v93, v62
	v_exp_f32_e32 v92, v94
	v_add_f32_e32 v50, v88, v50
	v_add_f32_e32 v51, v89, v51
	v_exp_f32_e32 v131, v63
	v_exp_f32_e32 v130, v95
	v_add_f32_e32 v50, v102, v50
	v_add_f32_e32 v51, v103, v51
	v_exp_f32_e32 v95, v64
	v_exp_f32_e32 v94, v96
	v_add_f32_e32 v50, v90, v50
	v_add_f32_e32 v51, v91, v51
	v_exp_f32_e32 v133, v65
	v_exp_f32_e32 v132, v97
	v_add_f32_e32 v50, v104, v50
	v_add_f32_e32 v51, v105, v51
	v_cvt_pk_bf16_f32 v54, v89, v103
	v_add_f32_e32 v50, v92, v50
	v_add_f32_e32 v51, v93, v51
	v_cvt_pk_bf16_f32 v55, v91, v105
	v_add_f32_e32 v50, v130, v50
	v_add_f32_e32 v51, v131, v51
	v_cvt_pk_bf16_f32 v56, v93, v131
	v_add_f32_e32 v50, v94, v50
	v_add_f32_e32 v51, v95, v51
	v_cvt_pk_bf16_f32 v57, v95, v133
	v_add_f32_e32 v50, v132, v50
	v_add_f32_e32 v51, v133, v51
	v_cvt_pk_bf16_f32 v60, v80, v82
	v_add_f32_e32 v96, v50, v51
	v_cvt_pk_bf16_f32 v51, v52, v53
	v_cvt_pk_bf16_f32 v52, v81, v83
	v_cvt_pk_bf16_f32 v53, v85, v87
	v_cvt_pk_bf16_f32 v61, v84, v86
	v_cvt_pk_bf16_f32 v62, v88, v102
	v_cvt_pk_bf16_f32 v63, v90, v104
	v_cvt_pk_bf16_f32 v64, v92, v130
	v_cvt_pk_bf16_f32 v65, v94, v132
	ds_read_b64_tr_b16 v[80:81], v214 offset:36864
	ds_read_b64_tr_b16 v[82:83], v214 offset:37376
	ds_read_b64_tr_b16 v[84:85], v214 offset:37888
	ds_read_b64_tr_b16 v[86:87], v214 offset:38400
	ds_read_b64_tr_b16 v[88:89], v214 offset:38912
	ds_read_b64_tr_b16 v[90:91], v214 offset:39424
	ds_read_b64_tr_b16 v[92:93], v214 offset:39936
	ds_read_b64_tr_b16 v[94:95], v214 offset:40448
	v_cvt_pk_bf16_f32 v50, v67, v135
	v_cvt_pk_bf16_f32 v58, v134, v136
	v_cvt_pk_bf16_f32 v59, v137, v138
	s_waitcnt lgkmcnt(0)
	v_mfma_f32_32x32x16_bf16 v[2:17], v[68:71], v[50:53], v[2:17]
	s_add_i32 s0, s75, 0xa000
	s_cmp_lt_i32 s75, 0x14000
	s_cselect_b32 s75, s0, 0
	s_addk_i32 s38, 0x80
	v_add_f32_e32 v231, v66, v96
	s_cmp_lg_u32 s13, 16
	v_mfma_f32_32x32x16_bf16 v[18:33], v[80:83], v[50:53], v[18:33]
	v_mfma_f32_32x32x16_bf16 v[2:17], v[72:75], v[54:57], v[2:17]
	v_mfma_f32_32x32x16_bf16 v[18:33], v[84:87], v[54:57], v[18:33]
	v_mfma_f32_32x32x16_bf16 v[2:17], v[76:79], v[58:61], v[2:17]
	v_mfma_f32_32x32x16_bf16 v[18:33], v[88:91], v[58:61], v[18:33]
	v_mfma_f32_32x32x16_bf16 v[2:17], v[98:101], v[62:65], v[2:17]
	v_mfma_f32_32x32x16_bf16 v[18:33], v[92:95], v[62:65], v[18:33]
	s_cbranch_scc0 .LBB0_517

.LBB0_536:
	s_waitcnt lgkmcnt(0)
	s_nop 0
	v_mfma_f32_32x32x16_bf16 v[50:65], v[182:185], v[106:109], v[34:49]
	v_exp_f32_e32 v183, v90
	v_exp_f32_e32 v182, v66
	v_exp_f32_e32 v91, v91
	v_add_f32_e32 v185, 0, v183
	v_add_f32_e32 v184, 0, v182
	v_cvt_pk_bf16_f32 v66, v183, v91
	v_mfma_f32_32x32x16_bf16 v[50:65], v[178:181], v[110:113], v[50:65]
	v_exp_f32_e32 v90, v67
	v_exp_f32_e32 v181, v92
	v_exp_f32_e32 v180, v68
	v_add_f32_e32 v184, v90, v184
	v_add_f32_e32 v185, v91, v185
	v_cvt_pk_bf16_f32 v178, v182, v90
	v_add_f32_e32 v90, v180, v184
	v_add_f32_e32 v91, v181, v185
	v_mfma_f32_32x32x16_bf16 v[50:65], v[174:177], v[114:117], v[50:65]
	v_exp_f32_e32 v93, v93
	v_exp_f32_e32 v92, v69
	v_exp_f32_e32 v175, v94
	v_cvt_pk_bf16_f32 v67, v181, v93
	v_add_f32_e32 v68, v92, v90
	v_add_f32_e32 v69, v93, v91
	v_cvt_pk_bf16_f32 v179, v180, v92
	v_mfma_f32_32x32x16_bf16 v[50:65], v[170:173], v[118:121], v[50:65]
	v_exp_f32_e32 v174, v70
	v_exp_f32_e32 v91, v95
	v_exp_f32_e32 v90, v71
	v_add_f32_e32 v70, v174, v68
	v_add_f32_e32 v71, v175, v69
	v_cvt_pk_bf16_f32 v68, v175, v91
	v_cvt_pk_bf16_f32 v180, v174, v90
	v_add_f32_e32 v70, v90, v70
	v_add_f32_e32 v71, v91, v71
	v_mfma_f32_32x32x16_bf16 v[50:65], v[86:89], v[122:125], v[50:65]
	v_exp_f32_e32 v87, v96
	v_exp_f32_e32 v86, v72
	v_exp_f32_e32 v89, v97
	v_add_f32_e32 v71, v87, v71
	v_add_f32_e32 v70, v86, v70
	v_cvt_pk_bf16_f32 v69, v87, v89
	v_mfma_f32_32x32x16_bf16 v[50:65], v[82:85], v[126:129], v[50:65]
	v_exp_f32_e32 v88, v73
	v_exp_f32_e32 v73, v98
	v_exp_f32_e32 v72, v74
	v_add_f32_e32 v70, v88, v70
	v_add_f32_e32 v71, v89, v71
	v_cvt_pk_bf16_f32 v181, v86, v88
	v_add_f32_e32 v71, v73, v71
	v_add_f32_e32 v70, v72, v70
	v_mfma_f32_32x32x16_bf16 v[82:97], v[166:169], v[106:109], v[34:49]
	v_exp_f32_e32 v99, v99
	v_exp_f32_e32 v98, v75
	v_exp_f32_e32 v167, v100
	v_add_f32_e32 v169, v99, v71
	v_add_f32_e32 v168, v98, v70
	v_cvt_pk_bf16_f32 v70, v73, v99
	v_cvt_pk_bf16_f32 v74, v72, v98
	v_mfma_f32_32x32x16_bf16 v[82:97], v[162:165], v[110:113], v[82:97]
	v_exp_f32_e32 v166, v76
	v_exp_f32_e32 v73, v101
	v_exp_f32_e32 v72, v77
	v_add_f32_e32 v76, v166, v168
	v_add_f32_e32 v77, v167, v169
	v_cvt_pk_bf16_f32 v71, v167, v73
	v_add_f32_e32 v77, v73, v77
	v_add_f32_e32 v76, v72, v76
	v_cvt_pk_bf16_f32 v75, v166, v72
	v_mfma_f32_32x32x16_bf16 v[82:97], v[158:161], v[114:117], v[82:97]
	v_exp_f32_e32 v99, v102
	v_exp_f32_e32 v98, v78
	v_exp_f32_e32 v101, v103
	v_add_f32_e32 v77, v99, v77
	v_add_f32_e32 v76, v98, v76
	v_cvt_pk_bf16_f32 v72, v99, v101
	v_mfma_f32_32x32x16_bf16 v[82:97], v[154:157], v[118:121], v[82:97]
	v_exp_f32_e32 v100, v79
	v_exp_f32_e32 v79, v104
	v_exp_f32_e32 v78, v80
	v_add_f32_e32 v76, v100, v76
	v_add_f32_e32 v77, v101, v77
	s_nop 0
	v_add_f32_e32 v103, v79, v77
	v_add_f32_e32 v102, v78, v76
	v_cvt_pk_bf16_f32 v76, v98, v100
	v_mfma_f32_32x32x16_bf16 v[82:97], v[150:153], v[122:125], v[82:97]
	v_exp_f32_e32 v99, v105
	v_exp_f32_e32 v98, v81
	v_cvt_pk_bf16_f32 v73, v79, v99
	v_add_f32_e32 v81, v99, v103
	v_add_f32_e32 v80, v98, v102
	v_cvt_pk_bf16_f32 v77, v78, v98
	v_add_f32_e32 v150, v80, v81
	v_mfma_f32_32x32x16_bf16 v[82:97], v[146:149], v[126:129], v[82:97]
	s_waitcnt vmcnt(0)
	s_barrier
	s_cmp_gt_u32 s13, 13
	s_cselect_b64 s[24:25], -1, 0
	s_and_b64 s[40:41], s[24:25], s[18:19]
	s_and_b64 vcc, exec, s[40:41]
	s_cbranch_vccnz .Lmla_nodma
	s_and_b64 s[24:25], s[24:25], exec
	s_movk_i32 s30, 0xf900
	s_cselect_b32 s25, s15, s9
	s_cselect_b32 s24, s14, s8
	s_cselect_b32 s0, s17, s11
	s_cselect_b32 s4, s16, s10
	s_cselect_b32 s30, s30, 0x100
	s_cmp_gt_i32 s75, 0x9fff
	s_cselect_b32 s31, s68, 0x14000
	s_add_i32 s31, s31, s75
	s_add_u32 s40, s51, s4
	s_addc_u32 s41, s71, s0
	s_add_u32 s54, s44, s24
	s_addc_u32 s55, s45, s25
	s_add_i32 s4, s30, s38
	v_lshl_add_u64 v[154:155], v[190:191], 0, s[4:5]
	s_add_i32 s0, s28, s31
	v_lshl_add_u64 v[152:153], v[216:217], 0, s[24:25]
	v_lshl_add_u64 v[154:155], v[154:155], 4, s[54:55]
	s_add_i32 s24, s4, s12
	s_mov_b32 m0, s0
	v_lshl_add_u64 v[156:157], v[186:187], 0, s[4:5]
	s_ashr_i32 s25, s24, 31
	global_load_lds_dwordx4 v[154:155], off
	v_lshl_add_u64 v[154:155], v[154:155], 0, s[26:27]
	s_add_i32 m0, s0, 0x400
	s_add_i32 s0, s29, s31
	v_lshl_add_u64 v[156:157], v[156:157], 4, s[40:41]
	s_lshl_b64 s[24:25], s[24:25], 6
	global_load_lds_dwordx4 v[154:155], off
	s_add_i32 m0, s0, 0x4000
	s_add_i32 s0, s37, s31
	v_lshl_add_u64 v[152:153], v[152:153], 0, s[24:25]
	global_load_lds_dwordx4 v[156:157], off
	s_add_i32 m0, s0, 0x6000
	s_nop 0
	global_load_lds_dwordx4 v[152:153], off
	v_lshl_add_u64 v[152:153], v[152:153], 0, s[48:49]
	s_add_i32 m0, s0, 0x8000
	s_nop 0
	global_load_lds_dwordx4 v[152:153], off
